# P4 row sum-of-squares all-reduce via permlane32/16 swap and DPP instead of six ds_bpermute rounds
# speedup vs baseline: 1.0095x; 1.0039x over previous
; DI float bflo(unsigned d) { return __uint_as_float(d << 16); }
; DI float bfhi(unsigned d) { return __uint_as_float(d & 0xffff0000u); }
; DI float siluf(float x) { return x / (1.f + __expf(-x)); }
; DI float wave_sum(float v) {
; #pragma unroll
;   for (int o = 32; o > 0; o >>= 1) v += __shfl_xor(v, o);
;   return v;
; DI void phase4(const Params& p) {
;     ...
;       unsigned ov = *(const unsigned*)&p.odn[(size_t)row * 512 + h * 128 + lane * 2];
;       unsigned zv = *(const unsigned*)&p.proj[(size_t)row * NP + 1536 + h * 128 + lane * 2];
;       float o0 = bflo(ov), o1 = bfhi(ov);
;       float ss = wave_sum(o0 * o0 + o1 * o1);
;       float rs = rsqrtf(ss * (1.f / 128.f) + EPS);
;       float2 gn = *(const float2*)&p.g_onorm[lane * 2];
;       float y0 = o0 * rs * gn.x * siluf(bflo(zv)), y1 = o1 * rs * gn.y * siluf(bfhi(zv));
.Lp4_goA:
	s_mov_b32 s11, 0
	v_lshlrev_b32_e32 v72, 16, v32
	v_and_b32_e32 v76, 0xffff0000, v32
	v_lshlrev_b32_e32 v80, 16, v36
	v_and_b32_e32 v84, 0xffff0000, v36
	v_mul_f32_e32 v88, v72, v72
	v_mul_f32_e32 v92, v76, v76
	v_add_f32_e32 v88, v88, v92
	v_lshlrev_b32_e32 v73, 16, v33
	v_and_b32_e32 v77, 0xffff0000, v33
	v_lshlrev_b32_e32 v81, 16, v37
	v_and_b32_e32 v85, 0xffff0000, v37
	v_mul_f32_e32 v89, v73, v73
	v_mul_f32_e32 v93, v77, v77
	v_add_f32_e32 v89, v89, v93
	v_lshlrev_b32_e32 v74, 16, v34
	v_and_b32_e32 v78, 0xffff0000, v34
	v_lshlrev_b32_e32 v82, 16, v38
	v_and_b32_e32 v86, 0xffff0000, v38
	v_mul_f32_e32 v90, v74, v74
	v_mul_f32_e32 v94, v78, v78
	v_add_f32_e32 v90, v90, v94
	v_lshlrev_b32_e32 v75, 16, v35
	v_and_b32_e32 v79, 0xffff0000, v35
	v_lshlrev_b32_e32 v83, 16, v39
	v_and_b32_e32 v87, 0xffff0000, v39
	v_mul_f32_e32 v91, v75, v75
	v_mul_f32_e32 v95, v79, v79
	v_add_f32_e32 v91, v91, v95
	v_mov_b32_e32 v92, v88
	v_mov_b32_e32 v93, v89
	v_mov_b32_e32 v94, v90
	v_mov_b32_e32 v95, v91
	s_nop 1
	v_permlane32_swap_b32 v88, v92
	v_permlane32_swap_b32 v89, v93
	v_permlane32_swap_b32 v90, v94
	v_permlane32_swap_b32 v91, v95
	s_nop 1
	v_add_f32_e32 v88, v88, v92
	v_add_f32_e32 v89, v89, v93
	v_add_f32_e32 v90, v90, v94
	v_add_f32_e32 v91, v91, v95
	v_mov_b32_e32 v92, v88
	v_mov_b32_e32 v93, v89
	v_mov_b32_e32 v94, v90
	v_mov_b32_e32 v95, v91
	s_nop 1
	v_permlane16_swap_b32 v88, v92
	v_permlane16_swap_b32 v89, v93
	v_permlane16_swap_b32 v90, v94
	v_permlane16_swap_b32 v91, v95
	s_nop 1
	v_add_f32_e32 v88, v88, v92
	v_add_f32_e32 v89, v89, v93
	v_add_f32_e32 v90, v90, v94
	v_add_f32_e32 v91, v91, v95
	s_nop 1
	v_add_f32_dpp v92, v88, v88 quad_perm:[1,0,3,2] row_mask:0xf bank_mask:0xf
	v_add_f32_dpp v93, v89, v89 quad_perm:[1,0,3,2] row_mask:0xf bank_mask:0xf
	v_add_f32_dpp v94, v90, v90 quad_perm:[1,0,3,2] row_mask:0xf bank_mask:0xf
	v_add_f32_dpp v95, v91, v91 quad_perm:[1,0,3,2] row_mask:0xf bank_mask:0xf
	s_nop 1
	v_add_f32_dpp v88, v92, v92 quad_perm:[2,3,0,1] row_mask:0xf bank_mask:0xf
	v_add_f32_dpp v89, v93, v93 quad_perm:[2,3,0,1] row_mask:0xf bank_mask:0xf
	v_add_f32_dpp v90, v94, v94 quad_perm:[2,3,0,1] row_mask:0xf bank_mask:0xf
	v_add_f32_dpp v91, v95, v95 quad_perm:[2,3,0,1] row_mask:0xf bank_mask:0xf
	s_nop 1
	v_add_f32_dpp v92, v88, v88 row_half_mirror row_mask:0xf bank_mask:0xf
	v_add_f32_dpp v93, v89, v89 row_half_mirror row_mask:0xf bank_mask:0xf
	v_add_f32_dpp v94, v90, v90 row_half_mirror row_mask:0xf bank_mask:0xf
	v_add_f32_dpp v95, v91, v91 row_half_mirror row_mask:0xf bank_mask:0xf
	s_nop 1
	v_add_f32_dpp v88, v92, v92 row_ror:8 row_mask:0xf bank_mask:0xf
	v_add_f32_dpp v89, v93, v93 row_ror:8 row_mask:0xf bank_mask:0xf
	v_add_f32_dpp v90, v94, v94 row_ror:8 row_mask:0xf bank_mask:0xf
	v_add_f32_dpp v91, v95, v95 row_ror:8 row_mask:0xf bank_mask:0xf
	s_nop 1
	v_mul_f32_e32 v109, 0xbfb8aa3b, v80
	v_exp_f32_e32 v109, v109
	s_nop 0
	v_add_f32_e32 v110, 1.0, v109
	v_div_scale_f32 v104, s[96:97], v110, v110, v80
	v_rcp_f32_e32 v105, v104
	v_div_scale_f32 v106, vcc, v80, v110, v80
	v_fma_f32 v107, -v104, v105, 1.0
	v_fmac_f32_e32 v105, v107, v105
	v_mul_f32_e32 v107, v106, v105
	v_fma_f32 v108, -v104, v107, v106
	v_fmac_f32_e32 v107, v108, v105
	v_fma_f32 v106, -v104, v107, v106
	v_div_fmas_f32 v106, v106, v105, v107
	v_div_fixup_f32 v96, v106, v110, v80
	v_mul_f32_e32 v109, 0xbfb8aa3b, v84
	v_exp_f32_e32 v109, v109
	s_nop 0
	v_add_f32_e32 v110, 1.0, v109
	v_div_scale_f32 v104, s[96:97], v110, v110, v84
	v_rcp_f32_e32 v105, v104
	v_div_scale_f32 v106, vcc, v84, v110, v84
	v_fma_f32 v107, -v104, v105, 1.0
	v_fmac_f32_e32 v105, v107, v105
	v_mul_f32_e32 v107, v106, v105
	v_fma_f32 v108, -v104, v107, v106
	v_fmac_f32_e32 v107, v108, v105
	v_fma_f32 v106, -v104, v107, v106
	v_div_fmas_f32 v106, v106, v105, v107
	v_div_fixup_f32 v100, v106, v110, v84
	v_mul_f32_e32 v109, 0xbfb8aa3b, v81
	v_exp_f32_e32 v109, v109
	s_nop 0
	v_add_f32_e32 v110, 1.0, v109
	v_div_scale_f32 v104, s[96:97], v110, v110, v81
	v_rcp_f32_e32 v105, v104
	v_div_scale_f32 v106, vcc, v81, v110, v81
	v_fma_f32 v107, -v104, v105, 1.0
	v_fmac_f32_e32 v105, v107, v105
	v_mul_f32_e32 v107, v106, v105
	v_fma_f32 v108, -v104, v107, v106
	v_fmac_f32_e32 v107, v108, v105
	v_fma_f32 v106, -v104, v107, v106
	v_div_fmas_f32 v106, v106, v105, v107
	v_div_fixup_f32 v97, v106, v110, v81
	v_mul_f32_e32 v109, 0xbfb8aa3b, v85
	v_exp_f32_e32 v109, v109
	s_nop 0
	v_add_f32_e32 v110, 1.0, v109
	v_div_scale_f32 v104, s[96:97], v110, v110, v85
	v_rcp_f32_e32 v105, v104
	v_div_scale_f32 v106, vcc, v85, v110, v85
	v_fma_f32 v107, -v104, v105, 1.0
	v_fmac_f32_e32 v105, v107, v105
	v_mul_f32_e32 v107, v106, v105
	v_fma_f32 v108, -v104, v107, v106
	v_fmac_f32_e32 v107, v108, v105
	v_fma_f32 v106, -v104, v107, v106
	v_div_fmas_f32 v106, v106, v105, v107
	v_div_fixup_f32 v101, v106, v110, v85
	v_mul_f32_e32 v109, 0xbfb8aa3b, v82
	v_exp_f32_e32 v109, v109
	s_nop 0
	v_add_f32_e32 v110, 1.0, v109
	v_div_scale_f32 v104, s[96:97], v110, v110, v82
	v_rcp_f32_e32 v105, v104
	v_div_scale_f32 v106, vcc, v82, v110, v82
	v_fma_f32 v107, -v104, v105, 1.0
	v_fmac_f32_e32 v105, v107, v105
	v_mul_f32_e32 v107, v106, v105
	v_fma_f32 v108, -v104, v107, v106
	v_fmac_f32_e32 v107, v108, v105
	v_fma_f32 v106, -v104, v107, v106
	v_div_fmas_f32 v106, v106, v105, v107
	v_div_fixup_f32 v98, v106, v110, v82
	v_mul_f32_e32 v109, 0xbfb8aa3b, v86
	v_exp_f32_e32 v109, v109
	s_nop 0
	v_add_f32_e32 v110, 1.0, v109
	v_div_scale_f32 v104, s[96:97], v110, v110, v86
	v_rcp_f32_e32 v105, v104
	v_div_scale_f32 v106, vcc, v86, v110, v86
	v_fma_f32 v107, -v104, v105, 1.0
	v_fmac_f32_e32 v105, v107, v105
; DI unsigned pack2(float a, float b) { return (unsigned)f2bf(a) | ((unsigned)f2bf(b) << 16); }
; DI float bflo(unsigned d) { return __uint_as_float(d << 16); }
; DI float bfhi(unsigned d) { return __uint_as_float(d & 0xffff0000u); }
; DI float siluf(float x) { return x / (1.f + __expf(-x)); }
; DI void phase4(const Params& p) {
;     ...
;       float ss = wave_sum(o0 * o0 + o1 * o1);
;       float rs = rsqrtf(ss * (1.f / 128.f) + EPS);
;       float2 gn = *(const float2*)&p.g_onorm[lane * 2];
;       float y0 = o0 * rs * gn.x * siluf(bflo(zv)), y1 = o1 * rs * gn.y * siluf(bfhi(zv));
;       *(unsigned*)&dst[h * 128 + lane * 2] = pack2(y0, y1);
;     }
;     {
;       const int h = lane >> 4;
;       float l0 = p.lse[((size_t)0 * MT + row) * 4 + h], l1 = p.lse[((size_t)1 * MT + row) * 4 + h], l2 = p.lse[((size_t)2 * MT + row) * 4 + h];
;       float m = fmaxf(l0, fmaxf(l1, l2));
;       float e0 = __expf(l0 - m), e1 = __expf(l1 - m), e2 = __expf(l2 - m);
;       float inv = 1.f / (e0 + e1 + e2);
;       uint2 a = *(const uint2*)&p.osw[((size_t)0 * MT + row) * 256 + lane * 4];
;       uint2 c = *(const uint2*)&p.osw[((size_t)1 * MT + row) * 256 + lane * 4];
;       uint2 d = *(const uint2*)&p.osw[((size_t)2 * MT + row) * 256 + lane * 4];
;       e0 *= inv; e1 *= inv; e2 *= inv;
;       float y0 = e0 * bflo(a.x) + e1 * bflo(c.x) + e2 * bflo(d.x);
;       float y1 = e0 * bfhi(a.x) + e1 * bfhi(c.x) + e2 * bfhi(d.x);
;       float y2 = e0 * bflo(a.y) + e1 * bflo(c.y) + e2 * bflo(d.y);
;       float y3 = e0 * bfhi(a.y) + e1 * bfhi(c.y) + e2 * bfhi(d.y);
;       *(uint2*)&dst[512 + lane * 4] = make_uint2(pack2(y0, y1), pack2(y2, y3));
	v_mul_f32_e32 v107, v106, v105
	v_fma_f32 v108, -v104, v107, v106
	v_fmac_f32_e32 v107, v108, v105
	v_fma_f32 v106, -v104, v107, v106
	v_div_fmas_f32 v106, v106, v105, v107
	v_div_fixup_f32 v102, v106, v110, v86
	v_mul_f32_e32 v109, 0xbfb8aa3b, v83
	v_exp_f32_e32 v109, v109
	s_nop 0
	v_add_f32_e32 v110, 1.0, v109
	v_div_scale_f32 v104, s[96:97], v110, v110, v83
	v_rcp_f32_e32 v105, v104
	v_div_scale_f32 v106, vcc, v83, v110, v83
	v_fma_f32 v107, -v104, v105, 1.0
	v_fmac_f32_e32 v105, v107, v105
	v_mul_f32_e32 v107, v106, v105
	v_fma_f32 v108, -v104, v107, v106
	v_fmac_f32_e32 v107, v108, v105
	v_fma_f32 v106, -v104, v107, v106
	v_div_fmas_f32 v106, v106, v105, v107
	v_div_fixup_f32 v99, v106, v110, v83
	v_mul_f32_e32 v109, 0xbfb8aa3b, v87
	v_exp_f32_e32 v109, v109
	s_nop 0
	v_add_f32_e32 v110, 1.0, v109
	v_div_scale_f32 v104, s[96:97], v110, v110, v87
	v_rcp_f32_e32 v105, v104
	v_div_scale_f32 v106, vcc, v87, v110, v87
	v_fma_f32 v107, -v104, v105, 1.0
	v_fmac_f32_e32 v105, v107, v105
	v_mul_f32_e32 v107, v106, v105
	v_fma_f32 v108, -v104, v107, v106
	v_fmac_f32_e32 v107, v108, v105
	v_fma_f32 v106, -v104, v107, v106
	v_div_fmas_f32 v106, v106, v105, v107
	v_div_fixup_f32 v103, v106, v110, v87
	v_fmamk_f32 v88, v88, 0x3c000000, v9
	v_mul_f32_e32 v92, 0x4b800000, v88
	v_cmp_gt_f32_e32 vcc, 0x800000, v88
	s_nop 1
	v_cndmask_b32_e32 v88, v88, v92, vcc
	v_rsq_f32_e32 v88, v88
	s_nop 0
	v_mul_f32_e32 v92, 0x45800000, v88
	v_cndmask_b32_e32 v88, v88, v92, vcc
	v_mul_f32_e32 v72, v88, v72
	v_mul_f32_e32 v76, v88, v76
	v_mul_f32_e32 v72, v18, v72
	v_mul_f32_e32 v76, v19, v76
	v_mul_f32_e32 v72, v96, v72
	v_mul_f32_e32 v76, v100, v76
	v_bfe_u32 v92, v72, 16, 1
	v_add3_u32 v72, v72, v92, s23
	v_bfe_u32 v92, v76, 16, 1
	v_add3_u32 v76, v76, v92, s23
	v_lshrrev_b32_e32 v72, 16, v72
	v_and_or_b32 v72, v76, s1, v72
	v_fmamk_f32 v89, v89, 0x3c000000, v9
	v_mul_f32_e32 v93, 0x4b800000, v89
	v_cmp_gt_f32_e32 vcc, 0x800000, v89
	s_nop 1
	v_cndmask_b32_e32 v89, v89, v93, vcc
	v_rsq_f32_e32 v89, v89
	s_nop 0
	v_mul_f32_e32 v93, 0x45800000, v89
	v_cndmask_b32_e32 v89, v89, v93, vcc
	v_mul_f32_e32 v73, v89, v73
	v_mul_f32_e32 v77, v89, v77
	v_mul_f32_e32 v73, v18, v73
	v_mul_f32_e32 v77, v19, v77
	v_mul_f32_e32 v73, v97, v73
	v_mul_f32_e32 v77, v101, v77
	v_bfe_u32 v93, v73, 16, 1
	v_add3_u32 v73, v73, v93, s23
	v_bfe_u32 v93, v77, 16, 1
	v_add3_u32 v77, v77, v93, s23
	v_lshrrev_b32_e32 v73, 16, v73
	v_and_or_b32 v73, v77, s1, v73
	v_fmamk_f32 v90, v90, 0x3c000000, v9
	v_mul_f32_e32 v94, 0x4b800000, v90
	v_cmp_gt_f32_e32 vcc, 0x800000, v90
	s_nop 1
	v_cndmask_b32_e32 v90, v90, v94, vcc
	v_rsq_f32_e32 v90, v90
	s_nop 0
	v_mul_f32_e32 v94, 0x45800000, v90
	v_cndmask_b32_e32 v90, v90, v94, vcc
	v_mul_f32_e32 v74, v90, v74
	v_mul_f32_e32 v78, v90, v78
	v_mul_f32_e32 v74, v18, v74
	v_mul_f32_e32 v78, v19, v78
	v_mul_f32_e32 v74, v98, v74
	v_mul_f32_e32 v78, v102, v78
	v_bfe_u32 v94, v74, 16, 1
	v_add3_u32 v74, v74, v94, s23
	v_bfe_u32 v94, v78, 16, 1
	v_add3_u32 v78, v78, v94, s23
	v_lshrrev_b32_e32 v74, 16, v74
	v_and_or_b32 v74, v78, s1, v74
	v_fmamk_f32 v91, v91, 0x3c000000, v9
	v_mul_f32_e32 v95, 0x4b800000, v91
	v_cmp_gt_f32_e32 vcc, 0x800000, v91
	s_nop 1
	v_cndmask_b32_e32 v91, v91, v95, vcc
	v_rsq_f32_e32 v91, v91
	s_nop 0
	v_mul_f32_e32 v95, 0x45800000, v91
	v_cndmask_b32_e32 v91, v91, v95, vcc
	v_mul_f32_e32 v75, v91, v75
	v_mul_f32_e32 v79, v91, v79
	v_mul_f32_e32 v75, v18, v75
	v_mul_f32_e32 v79, v19, v79
	v_mul_f32_e32 v75, v99, v75
	v_mul_f32_e32 v79, v103, v79
	v_bfe_u32 v95, v75, 16, 1
	v_add3_u32 v75, v75, v95, s23
	v_bfe_u32 v95, v79, 16, 1
	v_add3_u32 v79, v79, v95, s23
	v_lshrrev_b32_e32 v75, 16, v75
	v_and_or_b32 v75, v79, s1, v75
	v_max3_f32 v112, v40, v41, v42
	v_sub_f32_e32 v113, v40, v112
	v_mul_f32_e32 v113, 0x3fb8aa3b, v113
	v_sub_f32_e32 v114, v41, v112
	v_mul_f32_e32 v114, 0x3fb8aa3b, v114
	v_sub_f32_e32 v115, v42, v112
	v_mul_f32_e32 v115, 0x3fb8aa3b, v115
	v_exp_f32_e32 v113, v113
	v_exp_f32_e32 v114, v114
	v_exp_f32_e32 v115, v115
	s_nop 0
	v_add_f32_e32 v116, v113, v114
	v_add_f32_e32 v116, v115, v116
	v_mov_b32_e32 v117, 1.0
	v_div_scale_f32 v104, s[96:97], v116, v116, v117
	v_rcp_f32_e32 v105, v104
	v_div_scale_f32 v106, vcc, v117, v116, v117
	v_fma_f32 v107, -v104, v105, 1.0
	v_fmac_f32_e32 v105, v107, v105
	v_mul_f32_e32 v107, v106, v105
	v_fma_f32 v108, -v104, v107, v106
	v_fmac_f32_e32 v107, v108, v105
	v_fma_f32 v106, -v104, v107, v106
	v_div_fmas_f32 v106, v106, v105, v107
	v_div_fixup_f32 v118, v106, v116, v117
	v_mul_f32_e32 v113, v113, v118
	v_mul_f32_e32 v114, v114, v118
	v_mul_f32_e32 v115, v115, v118
	v_lshlrev_b32_e32 v124, 16, v44
	v_and_b32_e32 v125, 0xffff0000, v44
	v_lshlrev_b32_e32 v126, 16, v45
	v_and_b32_e32 v127, 0xffff0000, v45
	v_mul_f32_e32 v120, v113, v124
	v_mul_f32_e32 v121, v113, v125
	v_mul_f32_e32 v122, v113, v126
	v_mul_f32_e32 v123, v113, v127
	v_lshlrev_b32_e32 v124, 16, v46
	v_and_b32_e32 v125, 0xffff0000, v46
	v_lshlrev_b32_e32 v126, 16, v47
	v_and_b32_e32 v127, 0xffff0000, v47
	v_fmac_f32_e32 v120, v114, v124
	v_fmac_f32_e32 v121, v114, v125
	v_fmac_f32_e32 v122, v114, v126
	v_fmac_f32_e32 v123, v114, v127
	v_lshlrev_b32_e32 v124, 16, v48
	v_and_b32_e32 v125, 0xffff0000, v48
	v_lshlrev_b32_e32 v126, 16, v49
	v_and_b32_e32 v127, 0xffff0000, v49
	v_fmac_f32_e32 v120, v115, v124
	v_fmac_f32_e32 v121, v115, v125
	v_fmac_f32_e32 v122, v115, v126
	v_fmac_f32_e32 v123, v115, v127
	v_bfe_u32 v124, v120, 16, 1
	v_add3_u32 v120, v120, v124, s23
	v_bfe_u32 v125, v121, 16, 1
	v_add3_u32 v121, v121, v125, s23
	v_bfe_u32 v126, v122, 16, 1
	v_add3_u32 v122, v122, v126, s23
	v_bfe_u32 v127, v123, 16, 1
	v_add3_u32 v123, v123, v127, s23
	v_lshrrev_b32_e32 v120, 16, v120
	v_and_or_b32 v120, v121, s1, v120
	v_lshrrev_b32_e32 v122, 16, v122
	v_and_or_b32 v121, v123, s1, v122
	s_mul_i32 s0, s10, 0x600
	s_add_u32 s88, s14, s0
	s_addc_u32 s89, s15, 0
	global_store_dword v1, v72, s[88:89] offset:0
	global_store_dword v1, v73, s[88:89] offset:256
	global_store_dword v1, v74, s[88:89] offset:512
	global_store_dword v1, v75, s[88:89] offset:768
	global_store_dwordx2 v2, v[120:121], s[88:89] offset:1024
	s_mov_b32 s10, s22
	s_cmp_lt_i32 s10, 0x8080
	s_cbranch_scc0 .Lp4_done
; DI unsigned pack2(float a, float b) { return (unsigned)f2bf(a) | ((unsigned)f2bf(b) << 16); }
; DI float bflo(unsigned d) { return __uint_as_float(d << 16); }
; DI float bfhi(unsigned d) { return __uint_as_float(d & 0xffff0000u); }
; DI float siluf(float x) { return x / (1.f + __expf(-x)); }
; DI void phase4(const Params& p) {
;     ...
;   for (int row = blockIdx.x * 4 + w; row < MT; row += gridDim.x * 4) {
;     u16* dst = p.Amix + (size_t)row * 768;
; #pragma unroll
;     for (int h = 0; h < 4; ++h) {
;       unsigned ov = *(const unsigned*)&p.odn[(size_t)row * 512 + h * 128 + lane * 2];
;       unsigned zv = *(const unsigned*)&p.proj[(size_t)row * NP + 1536 + h * 128 + lane * 2];
;       float o0 = bflo(ov), o1 = bfhi(ov);
;       float ss = wave_sum(o0 * o0 + o1 * o1);
;       float rs = rsqrtf(ss * (1.f / 128.f) + EPS);
;       float2 gn = *(const float2*)&p.g_onorm[lane * 2];
;       float y0 = o0 * rs * gn.x * siluf(bflo(zv)), y1 = o1 * rs * gn.y * siluf(bfhi(zv));
;       *(unsigned*)&dst[h * 128 + lane * 2] = pack2(y0, y1);
;     }
;     {
;       const int h = lane >> 4;
;       float l0 = p.lse[((size_t)0 * MT + row) * 4 + h], l1 = p.lse[((size_t)1 * MT + row) * 4 + h], l2 = p.lse[((size_t)2 * MT + row) * 4 + h];
;       float m = fmaxf(l0, fmaxf(l1, l2));
;       float e0 = __expf(l0 - m), e1 = __expf(l1 - m), e2 = __expf(l2 - m);
;       float inv = 1.f / (e0 + e1 + e2);
;       uint2 a = *(const uint2*)&p.osw[((size_t)0 * MT + row) * 256 + lane * 4];
;       uint2 c = *(const uint2*)&p.osw[((size_t)1 * MT + row) * 256 + lane * 4];
;       uint2 d = *(const uint2*)&p.osw[((size_t)2 * MT + row) * 256 + lane * 4];
	s_add_i32 s22, s10, s78
	s_cmp_lt_i32 s22, 0x8080
	s_cbranch_scc0 .Lp4_lastB
	s_lshl_b32 s0, s22, 10
	s_add_u32 s92, s12, s0
	s_addc_u32 s93, s13, 0
	s_mul_i32 s0, s22, 0x2200
	s_add_u32 s0, s0, 0xc00
	s_add_u32 s94, s20, s0
	s_addc_u32 s95, s21, 0
	s_lshl_b32 s0, s22, 4
	s_add_u32 s96, s18, s0
	s_addc_u32 s97, s19, 0
	s_lshl_b32 s0, s22, 9
	s_add_u32 s90, s16, s0
	s_addc_u32 s91, s17, 0
	global_load_dword v32, v1, s[92:93] offset:0
	global_load_dword v33, v1, s[92:93] offset:256
	global_load_dword v34, v1, s[92:93] offset:512
	global_load_dword v35, v1, s[92:93] offset:768
	global_load_dword v36, v1, s[94:95] offset:0
	global_load_dword v37, v1, s[94:95] offset:256
	global_load_dword v38, v1, s[94:95] offset:512
	global_load_dword v39, v1, s[94:95] offset:768
	global_load_dword v40, v3, s[96:97]
	global_load_dword v41, v4, s[96:97]
	global_load_dword v42, v5, s[96:97]
	global_load_dwordx2 v[44:45], v6, s[90:91]
	global_load_dwordx2 v[46:47], v7, s[90:91]
	global_load_dwordx2 v[48:49], v8, s[90:91]
	s_waitcnt vmcnt(19)
	s_branch .Lp4_goB

; DI float bflo(unsigned d) { return __uint_as_float(d << 16); }
; DI float bfhi(unsigned d) { return __uint_as_float(d & 0xffff0000u); }
; DI float siluf(float x) { return x / (1.f + __expf(-x)); }
; DI float wave_sum(float v) {
; #pragma unroll
;   for (int o = 32; o > 0; o >>= 1) v += __shfl_xor(v, o);
;   return v;
; DI void phase4(const Params& p) {
;     ...
;       unsigned ov = *(const unsigned*)&p.odn[(size_t)row * 512 + h * 128 + lane * 2];
;       unsigned zv = *(const unsigned*)&p.proj[(size_t)row * NP + 1536 + h * 128 + lane * 2];
;       float o0 = bflo(ov), o1 = bfhi(ov);
;       float ss = wave_sum(o0 * o0 + o1 * o1);
;       float rs = rsqrtf(ss * (1.f / 128.f) + EPS);
;       float2 gn = *(const float2*)&p.g_onorm[lane * 2];
;       float y0 = o0 * rs * gn.x * siluf(bflo(zv)), y1 = o1 * rs * gn.y * siluf(bfhi(zv));
.Lp4_goB:
	v_lshlrev_b32_e32 v72, 16, v52
	v_and_b32_e32 v76, 0xffff0000, v52
	v_lshlrev_b32_e32 v80, 16, v56
	v_and_b32_e32 v84, 0xffff0000, v56
	v_mul_f32_e32 v88, v72, v72
	v_mul_f32_e32 v92, v76, v76
	v_add_f32_e32 v88, v88, v92
	v_lshlrev_b32_e32 v73, 16, v53
	v_and_b32_e32 v77, 0xffff0000, v53
	v_lshlrev_b32_e32 v81, 16, v57
	v_and_b32_e32 v85, 0xffff0000, v57
	v_mul_f32_e32 v89, v73, v73
	v_mul_f32_e32 v93, v77, v77
	v_add_f32_e32 v89, v89, v93
	v_lshlrev_b32_e32 v74, 16, v54
	v_and_b32_e32 v78, 0xffff0000, v54
	v_lshlrev_b32_e32 v82, 16, v58
	v_and_b32_e32 v86, 0xffff0000, v58
	v_mul_f32_e32 v90, v74, v74
	v_mul_f32_e32 v94, v78, v78
	v_add_f32_e32 v90, v90, v94
	v_lshlrev_b32_e32 v75, 16, v55
	v_and_b32_e32 v79, 0xffff0000, v55
	v_lshlrev_b32_e32 v83, 16, v59
	v_and_b32_e32 v87, 0xffff0000, v59
	v_mul_f32_e32 v91, v75, v75
	v_mul_f32_e32 v95, v79, v79
	v_add_f32_e32 v91, v91, v95
	v_mov_b32_e32 v92, v88
	v_mov_b32_e32 v93, v89
	v_mov_b32_e32 v94, v90
	v_mov_b32_e32 v95, v91
	s_nop 1
	v_permlane32_swap_b32 v88, v92
	v_permlane32_swap_b32 v89, v93
	v_permlane32_swap_b32 v90, v94
	v_permlane32_swap_b32 v91, v95
	s_nop 1
	v_add_f32_e32 v88, v88, v92
	v_add_f32_e32 v89, v89, v93
	v_add_f32_e32 v90, v90, v94
	v_add_f32_e32 v91, v91, v95
	v_mov_b32_e32 v92, v88
	v_mov_b32_e32 v93, v89
	v_mov_b32_e32 v94, v90
	v_mov_b32_e32 v95, v91
	s_nop 1
	v_permlane16_swap_b32 v88, v92
	v_permlane16_swap_b32 v89, v93
	v_permlane16_swap_b32 v90, v94
	v_permlane16_swap_b32 v91, v95
	s_nop 1
	v_add_f32_e32 v88, v88, v92
	v_add_f32_e32 v89, v89, v93
	v_add_f32_e32 v90, v90, v94
	v_add_f32_e32 v91, v91, v95
	s_nop 1
	v_add_f32_dpp v92, v88, v88 quad_perm:[1,0,3,2] row_mask:0xf bank_mask:0xf
	v_add_f32_dpp v93, v89, v89 quad_perm:[1,0,3,2] row_mask:0xf bank_mask:0xf
	v_add_f32_dpp v94, v90, v90 quad_perm:[1,0,3,2] row_mask:0xf bank_mask:0xf
	v_add_f32_dpp v95, v91, v91 quad_perm:[1,0,3,2] row_mask:0xf bank_mask:0xf
	s_nop 1
	v_add_f32_dpp v88, v92, v92 quad_perm:[2,3,0,1] row_mask:0xf bank_mask:0xf
	v_add_f32_dpp v89, v93, v93 quad_perm:[2,3,0,1] row_mask:0xf bank_mask:0xf
	v_add_f32_dpp v90, v94, v94 quad_perm:[2,3,0,1] row_mask:0xf bank_mask:0xf
	v_add_f32_dpp v91, v95, v95 quad_perm:[2,3,0,1] row_mask:0xf bank_mask:0xf
	s_nop 1
	v_add_f32_dpp v92, v88, v88 row_half_mirror row_mask:0xf bank_mask:0xf
	v_add_f32_dpp v93, v89, v89 row_half_mirror row_mask:0xf bank_mask:0xf
	v_add_f32_dpp v94, v90, v90 row_half_mirror row_mask:0xf bank_mask:0xf
	v_add_f32_dpp v95, v91, v91 row_half_mirror row_mask:0xf bank_mask:0xf
	s_nop 1
	v_add_f32_dpp v88, v92, v92 row_ror:8 row_mask:0xf bank_mask:0xf
	v_add_f32_dpp v89, v93, v93 row_ror:8 row_mask:0xf bank_mask:0xf
	v_add_f32_dpp v90, v94, v94 row_ror:8 row_mask:0xf bank_mask:0xf
	v_add_f32_dpp v91, v95, v95 row_ror:8 row_mask:0xf bank_mask:0xf
	s_nop 1
	v_mul_f32_e32 v109, 0xbfb8aa3b, v80
	v_exp_f32_e32 v109, v109
	s_nop 0
	v_add_f32_e32 v110, 1.0, v109
	v_div_scale_f32 v104, s[96:97], v110, v110, v80
	v_rcp_f32_e32 v105, v104
	v_div_scale_f32 v106, vcc, v80, v110, v80
	v_fma_f32 v107, -v104, v105, 1.0
	v_fmac_f32_e32 v105, v107, v105
	v_mul_f32_e32 v107, v106, v105
	v_fma_f32 v108, -v104, v107, v106
	v_fmac_f32_e32 v107, v108, v105
	v_fma_f32 v106, -v104, v107, v106
	v_div_fmas_f32 v106, v106, v105, v107
	v_div_fixup_f32 v96, v106, v110, v80
	v_mul_f32_e32 v109, 0xbfb8aa3b, v84
	v_exp_f32_e32 v109, v109
	s_nop 0
	v_add_f32_e32 v110, 1.0, v109
	v_div_scale_f32 v104, s[96:97], v110, v110, v84
	v_rcp_f32_e32 v105, v104
	v_div_scale_f32 v106, vcc, v84, v110, v84
	v_fma_f32 v107, -v104, v105, 1.0
	v_fmac_f32_e32 v105, v107, v105
	v_mul_f32_e32 v107, v106, v105
	v_fma_f32 v108, -v104, v107, v106
	v_fmac_f32_e32 v107, v108, v105
	v_fma_f32 v106, -v104, v107, v106
	v_div_fmas_f32 v106, v106, v105, v107
	v_div_fixup_f32 v100, v106, v110, v84
	v_mul_f32_e32 v109, 0xbfb8aa3b, v81
	v_exp_f32_e32 v109, v109
	s_nop 0
	v_add_f32_e32 v110, 1.0, v109
	v_div_scale_f32 v104, s[96:97], v110, v110, v81
	v_rcp_f32_e32 v105, v104
	v_div_scale_f32 v106, vcc, v81, v110, v81
	v_fma_f32 v107, -v104, v105, 1.0
	v_fmac_f32_e32 v105, v107, v105
	v_mul_f32_e32 v107, v106, v105
	v_fma_f32 v108, -v104, v107, v106
	v_fmac_f32_e32 v107, v108, v105
	v_fma_f32 v106, -v104, v107, v106
	v_div_fmas_f32 v106, v106, v105, v107
	v_div_fixup_f32 v97, v106, v110, v81
	v_mul_f32_e32 v109, 0xbfb8aa3b, v85
	v_exp_f32_e32 v109, v109
	s_nop 0
	v_add_f32_e32 v110, 1.0, v109
	v_div_scale_f32 v104, s[96:97], v110, v110, v85
	v_rcp_f32_e32 v105, v104
	v_div_scale_f32 v106, vcc, v85, v110, v85
	v_fma_f32 v107, -v104, v105, 1.0
	v_fmac_f32_e32 v105, v107, v105
	v_mul_f32_e32 v107, v106, v105
	v_fma_f32 v108, -v104, v107, v106
	v_fmac_f32_e32 v107, v108, v105
	v_fma_f32 v106, -v104, v107, v106
	v_div_fmas_f32 v106, v106, v105, v107
	v_div_fixup_f32 v101, v106, v110, v85
	v_mul_f32_e32 v109, 0xbfb8aa3b, v82
	v_exp_f32_e32 v109, v109
	s_nop 0
	v_add_f32_e32 v110, 1.0, v109
	v_div_scale_f32 v104, s[96:97], v110, v110, v82
	v_rcp_f32_e32 v105, v104
	v_div_scale_f32 v106, vcc, v82, v110, v82
	v_fma_f32 v107, -v104, v105, 1.0
	v_fmac_f32_e32 v105, v107, v105
	v_mul_f32_e32 v107, v106, v105
	v_fma_f32 v108, -v104, v107, v106
	v_fmac_f32_e32 v107, v108, v105
	v_fma_f32 v106, -v104, v107, v106
	v_div_fmas_f32 v106, v106, v105, v107
	v_div_fixup_f32 v98, v106, v110, v82
	v_mul_f32_e32 v109, 0xbfb8aa3b, v86
	v_exp_f32_e32 v109, v109
	s_nop 0
	v_add_f32_e32 v110, 1.0, v109
	v_div_scale_f32 v104, s[96:97], v110, v110, v86
	v_rcp_f32_e32 v105, v104
	v_div_scale_f32 v106, vcc, v86, v110, v86
	v_fma_f32 v107, -v104, v105, 1.0
	v_fmac_f32_e32 v105, v107, v105
	v_mul_f32_e32 v107, v106, v105
; DI unsigned pack2(float a, float b) { return (unsigned)f2bf(a) | ((unsigned)f2bf(b) << 16); }
; DI float bflo(unsigned d) { return __uint_as_float(d << 16); }
; DI float bfhi(unsigned d) { return __uint_as_float(d & 0xffff0000u); }
; DI float siluf(float x) { return x / (1.f + __expf(-x)); }
; DI void phase4(const Params& p) {
;     ...
;       float ss = wave_sum(o0 * o0 + o1 * o1);
;       float rs = rsqrtf(ss * (1.f / 128.f) + EPS);
;       float2 gn = *(const float2*)&p.g_onorm[lane * 2];
;       float y0 = o0 * rs * gn.x * siluf(bflo(zv)), y1 = o1 * rs * gn.y * siluf(bfhi(zv));
;       *(unsigned*)&dst[h * 128 + lane * 2] = pack2(y0, y1);
;     }
;     {
;       const int h = lane >> 4;
;       float l0 = p.lse[((size_t)0 * MT + row) * 4 + h], l1 = p.lse[((size_t)1 * MT + row) * 4 + h], l2 = p.lse[((size_t)2 * MT + row) * 4 + h];
;       float m = fmaxf(l0, fmaxf(l1, l2));
;       float e0 = __expf(l0 - m), e1 = __expf(l1 - m), e2 = __expf(l2 - m);
;       float inv = 1.f / (e0 + e1 + e2);
;       uint2 a = *(const uint2*)&p.osw[((size_t)0 * MT + row) * 256 + lane * 4];
;       uint2 c = *(const uint2*)&p.osw[((size_t)1 * MT + row) * 256 + lane * 4];
;       uint2 d = *(const uint2*)&p.osw[((size_t)2 * MT + row) * 256 + lane * 4];
;       e0 *= inv; e1 *= inv; e2 *= inv;
;       float y0 = e0 * bflo(a.x) + e1 * bflo(c.x) + e2 * bflo(d.x);
;       float y1 = e0 * bfhi(a.x) + e1 * bfhi(c.x) + e2 * bfhi(d.x);
;       float y2 = e0 * bflo(a.y) + e1 * bflo(c.y) + e2 * bflo(d.y);
;       float y3 = e0 * bfhi(a.y) + e1 * bfhi(c.y) + e2 * bfhi(d.y);
;       *(uint2*)&dst[512 + lane * 4] = make_uint2(pack2(y0, y1), pack2(y2, y3));
;     }
;   }
	v_fma_f32 v108, -v104, v107, v106
	v_fmac_f32_e32 v107, v108, v105
	v_fma_f32 v106, -v104, v107, v106
	v_div_fmas_f32 v106, v106, v105, v107
	v_div_fixup_f32 v102, v106, v110, v86
	v_mul_f32_e32 v109, 0xbfb8aa3b, v83
	v_exp_f32_e32 v109, v109
	s_nop 0
	v_add_f32_e32 v110, 1.0, v109
	v_div_scale_f32 v104, s[96:97], v110, v110, v83
	v_rcp_f32_e32 v105, v104
	v_div_scale_f32 v106, vcc, v83, v110, v83
	v_fma_f32 v107, -v104, v105, 1.0
	v_fmac_f32_e32 v105, v107, v105
	v_mul_f32_e32 v107, v106, v105
	v_fma_f32 v108, -v104, v107, v106
	v_fmac_f32_e32 v107, v108, v105
	v_fma_f32 v106, -v104, v107, v106
	v_div_fmas_f32 v106, v106, v105, v107
	v_div_fixup_f32 v99, v106, v110, v83
	v_mul_f32_e32 v109, 0xbfb8aa3b, v87
	v_exp_f32_e32 v109, v109
	s_nop 0
	v_add_f32_e32 v110, 1.0, v109
	v_div_scale_f32 v104, s[96:97], v110, v110, v87
	v_rcp_f32_e32 v105, v104
	v_div_scale_f32 v106, vcc, v87, v110, v87
	v_fma_f32 v107, -v104, v105, 1.0
	v_fmac_f32_e32 v105, v107, v105
	v_mul_f32_e32 v107, v106, v105
	v_fma_f32 v108, -v104, v107, v106
	v_fmac_f32_e32 v107, v108, v105
	v_fma_f32 v106, -v104, v107, v106
	v_div_fmas_f32 v106, v106, v105, v107
	v_div_fixup_f32 v103, v106, v110, v87
	v_fmamk_f32 v88, v88, 0x3c000000, v9
	v_mul_f32_e32 v92, 0x4b800000, v88
	v_cmp_gt_f32_e32 vcc, 0x800000, v88
	s_nop 1
	v_cndmask_b32_e32 v88, v88, v92, vcc
	v_rsq_f32_e32 v88, v88
	s_nop 0
	v_mul_f32_e32 v92, 0x45800000, v88
	v_cndmask_b32_e32 v88, v88, v92, vcc
	v_mul_f32_e32 v72, v88, v72
	v_mul_f32_e32 v76, v88, v76
	v_mul_f32_e32 v72, v18, v72
	v_mul_f32_e32 v76, v19, v76
	v_mul_f32_e32 v72, v96, v72
	v_mul_f32_e32 v76, v100, v76
	v_bfe_u32 v92, v72, 16, 1
	v_add3_u32 v72, v72, v92, s23
	v_bfe_u32 v92, v76, 16, 1
	v_add3_u32 v76, v76, v92, s23
	v_lshrrev_b32_e32 v72, 16, v72
	v_and_or_b32 v72, v76, s1, v72
	v_fmamk_f32 v89, v89, 0x3c000000, v9
	v_mul_f32_e32 v93, 0x4b800000, v89
	v_cmp_gt_f32_e32 vcc, 0x800000, v89
	s_nop 1
	v_cndmask_b32_e32 v89, v89, v93, vcc
	v_rsq_f32_e32 v89, v89
	s_nop 0
	v_mul_f32_e32 v93, 0x45800000, v89
	v_cndmask_b32_e32 v89, v89, v93, vcc
	v_mul_f32_e32 v73, v89, v73
	v_mul_f32_e32 v77, v89, v77
	v_mul_f32_e32 v73, v18, v73
	v_mul_f32_e32 v77, v19, v77
	v_mul_f32_e32 v73, v97, v73
	v_mul_f32_e32 v77, v101, v77
	v_bfe_u32 v93, v73, 16, 1
	v_add3_u32 v73, v73, v93, s23
	v_bfe_u32 v93, v77, 16, 1
	v_add3_u32 v77, v77, v93, s23
	v_lshrrev_b32_e32 v73, 16, v73
	v_and_or_b32 v73, v77, s1, v73
	v_fmamk_f32 v90, v90, 0x3c000000, v9
	v_mul_f32_e32 v94, 0x4b800000, v90
	v_cmp_gt_f32_e32 vcc, 0x800000, v90
	s_nop 1
	v_cndmask_b32_e32 v90, v90, v94, vcc
	v_rsq_f32_e32 v90, v90
	s_nop 0
	v_mul_f32_e32 v94, 0x45800000, v90
	v_cndmask_b32_e32 v90, v90, v94, vcc
	v_mul_f32_e32 v74, v90, v74
	v_mul_f32_e32 v78, v90, v78
	v_mul_f32_e32 v74, v18, v74
	v_mul_f32_e32 v78, v19, v78
	v_mul_f32_e32 v74, v98, v74
	v_mul_f32_e32 v78, v102, v78
	v_bfe_u32 v94, v74, 16, 1
	v_add3_u32 v74, v74, v94, s23
	v_bfe_u32 v94, v78, 16, 1
	v_add3_u32 v78, v78, v94, s23
	v_lshrrev_b32_e32 v74, 16, v74
	v_and_or_b32 v74, v78, s1, v74
	v_fmamk_f32 v91, v91, 0x3c000000, v9
	v_mul_f32_e32 v95, 0x4b800000, v91
	v_cmp_gt_f32_e32 vcc, 0x800000, v91
	s_nop 1
	v_cndmask_b32_e32 v91, v91, v95, vcc
	v_rsq_f32_e32 v91, v91
	s_nop 0
	v_mul_f32_e32 v95, 0x45800000, v91
	v_cndmask_b32_e32 v91, v91, v95, vcc
	v_mul_f32_e32 v75, v91, v75
	v_mul_f32_e32 v79, v91, v79
	v_mul_f32_e32 v75, v18, v75
	v_mul_f32_e32 v79, v19, v79
	v_mul_f32_e32 v75, v99, v75
	v_mul_f32_e32 v79, v103, v79
	v_bfe_u32 v95, v75, 16, 1
	v_add3_u32 v75, v75, v95, s23
	v_bfe_u32 v95, v79, 16, 1
	v_add3_u32 v79, v79, v95, s23
	v_lshrrev_b32_e32 v75, 16, v75
	v_and_or_b32 v75, v79, s1, v75
	v_max3_f32 v112, v60, v61, v62
	v_sub_f32_e32 v113, v60, v112
	v_mul_f32_e32 v113, 0x3fb8aa3b, v113
	v_sub_f32_e32 v114, v61, v112
	v_mul_f32_e32 v114, 0x3fb8aa3b, v114
	v_sub_f32_e32 v115, v62, v112
	v_mul_f32_e32 v115, 0x3fb8aa3b, v115
	v_exp_f32_e32 v113, v113
	v_exp_f32_e32 v114, v114
	v_exp_f32_e32 v115, v115
	s_nop 0
	v_add_f32_e32 v116, v113, v114
	v_add_f32_e32 v116, v115, v116
	v_mov_b32_e32 v117, 1.0
	v_div_scale_f32 v104, s[96:97], v116, v116, v117
	v_rcp_f32_e32 v105, v104
	v_div_scale_f32 v106, vcc, v117, v116, v117
	v_fma_f32 v107, -v104, v105, 1.0
	v_fmac_f32_e32 v105, v107, v105
	v_mul_f32_e32 v107, v106, v105
	v_fma_f32 v108, -v104, v107, v106
	v_fmac_f32_e32 v107, v108, v105
	v_fma_f32 v106, -v104, v107, v106
	v_div_fmas_f32 v106, v106, v105, v107
	v_div_fixup_f32 v118, v106, v116, v117
	v_mul_f32_e32 v113, v113, v118
	v_mul_f32_e32 v114, v114, v118
	v_mul_f32_e32 v115, v115, v118
	v_lshlrev_b32_e32 v124, 16, v64
	v_and_b32_e32 v125, 0xffff0000, v64
	v_lshlrev_b32_e32 v126, 16, v65
	v_and_b32_e32 v127, 0xffff0000, v65
	v_mul_f32_e32 v120, v113, v124
	v_mul_f32_e32 v121, v113, v125
	v_mul_f32_e32 v122, v113, v126
	v_mul_f32_e32 v123, v113, v127
	v_lshlrev_b32_e32 v124, 16, v66
	v_and_b32_e32 v125, 0xffff0000, v66
	v_lshlrev_b32_e32 v126, 16, v67
	v_and_b32_e32 v127, 0xffff0000, v67
	v_fmac_f32_e32 v120, v114, v124
	v_fmac_f32_e32 v121, v114, v125
	v_fmac_f32_e32 v122, v114, v126
	v_fmac_f32_e32 v123, v114, v127
	v_lshlrev_b32_e32 v124, 16, v68
	v_and_b32_e32 v125, 0xffff0000, v68
	v_lshlrev_b32_e32 v126, 16, v69
	v_and_b32_e32 v127, 0xffff0000, v69
	v_fmac_f32_e32 v120, v115, v124
	v_fmac_f32_e32 v121, v115, v125
	v_fmac_f32_e32 v122, v115, v126
	v_fmac_f32_e32 v123, v115, v127
	v_bfe_u32 v124, v120, 16, 1
	v_add3_u32 v120, v120, v124, s23
	v_bfe_u32 v125, v121, 16, 1
	v_add3_u32 v121, v121, v125, s23
	v_bfe_u32 v126, v122, 16, 1
	v_add3_u32 v122, v122, v126, s23
	v_bfe_u32 v127, v123, 16, 1
	v_add3_u32 v123, v123, v127, s23
	v_lshrrev_b32_e32 v120, 16, v120
	v_and_or_b32 v120, v121, s1, v120
	v_lshrrev_b32_e32 v122, 16, v122
	v_and_or_b32 v121, v123, s1, v122
	s_mul_i32 s0, s10, 0x600
	s_add_u32 s88, s14, s0
	s_addc_u32 s89, s15, 0
	global_store_dword v1, v72, s[88:89] offset:0
	global_store_dword v1, v73, s[88:89] offset:256
	global_store_dword v1, v74, s[88:89] offset:512
	global_store_dword v1, v75, s[88:89] offset:768
	global_store_dwordx2 v2, v[120:121], s[88:89] offset:1024
	s_mov_b32 s10, s22
	s_cmp_lt_i32 s10, 0x8080
	s_cbranch_scc1 .Lp4_loop
